# attention: each unit's first three K/V tile DMAs issued at the top of the unit prologue, ahead of the q-row loads
# speedup vs baseline: 1.0041x; 1.0041x over previous
.LBB0_800:
	v_mov_b32_e32 v205, v196
	v_mov_b32_e32 v5, 0
	v_ashrrev_i32_e32 v189, 6, v205
	v_and_b32_e32 v206, 63, v205
	v_lshlrev_b32_e32 v6, 4, v206
	v_lshlrev_b32_e32 v7, 10, v189
	v_or_b32_e32 v0, v7, v6
	v_mul_hi_i32 v1, v0, s72
	v_lshrrev_b32_e32 v2, 31, v1
	v_ashrrev_i32_e32 v1, 6, v1
	v_add_u32_e32 v1, v1, v2
	v_mad_u64_u32 v[2:3], s[4:5], v1, s73, v[0:1]
	v_cmp_gt_i32_e32 vcc, s75, v2
	s_and_saveexec_b64 s[4:5], vcc
	v_and_b32_e32 v3, 35, v1
	v_lshlrev_b32_e32 v4, 2, v1
	v_lshrrev_b32_e32 v1, 1, v1
	v_and_b32_e32 v4, 16, v4
	v_and_b32_e32 v1, 12, v1
	v_or3_b32 v1, v3, v4, v1
	v_mad_u32_u24 v5, v1, s75, v2
	s_or_b64 exec, exec, s[4:5]
	s_movk_i32 s3, 0x2000
	v_add3_u32 v4, v7, v6, s3
	v_mul_hi_i32 v1, v4, s72
	v_lshrrev_b32_e32 v2, 31, v1
	v_ashrrev_i32_e32 v1, 6, v1
	v_add_u32_e32 v8, v1, v2
	v_mad_u64_u32 v[2:3], s[4:5], v8, s73, v[4:5]
	v_cmp_gt_i32_e32 vcc, s75, v2
	v_mov_b32_e32 v1, 0
	v_mov_b32_e32 v3, 0
	s_and_saveexec_b64 s[4:5], vcc
	v_and_b32_e32 v3, 35, v8
	v_lshlrev_b32_e32 v9, 2, v8
	v_lshrrev_b32_e32 v8, 1, v8
	v_and_b32_e32 v9, 16, v9
	v_and_b32_e32 v8, 12, v8
	v_or3_b32 v3, v3, v9, v8
	v_mad_u32_u24 v3, v3, s75, v2
	s_or_b64 exec, exec, s[4:5]
	v_add3_u32 v2, v7, v6, s77
	v_mul_hi_i32 v6, v2, s72
	v_lshrrev_b32_e32 v7, 31, v6
	v_ashrrev_i32_e32 v6, 6, v6
	v_add_u32_e32 v8, v6, v7
	v_mad_u64_u32 v[6:7], s[4:5], v8, s73, v[2:3]
	v_cmp_gt_i32_e32 vcc, s75, v6
	s_and_saveexec_b64 s[4:5], vcc
	v_and_b32_e32 v1, 35, v8
	v_lshlrev_b32_e32 v7, 2, v8
	v_lshrrev_b32_e32 v8, 1, v8
	v_and_b32_e32 v7, 16, v7
	v_and_b32_e32 v8, 12, v8
	v_or3_b32 v1, v1, v7, v8
	v_mad_u32_u24 v1, v1, s75, v6
	s_or_b64 exec, exec, s[4:5]
	v_add_u32_e32 v4, 0xffffcc00, v4
	v_mul_hi_i32 v6, v4, s78
	v_lshrrev_b32_e32 v7, 31, v6
	v_ashrrev_i32_e32 v6, 5, v6
	v_add_u32_e32 v8, v6, v7
	v_mad_u64_u32 v[6:7], s[4:5], v8, s79, v[4:5]
	v_lshl_add_u32 v4, v8, 6, v6
	v_cmp_gt_i32_e32 vcc, 64, v6
	v_add_u32_e32 v0, 0xffffcc00, v0
	s_lshl_b32 s3, s2, 8
	v_cndmask_b32_e32 v4, 0, v4, vcc
	v_cmp_gt_i32_e32 vcc, 5, v189
	s_and_b32 s3, s3, 0x1f00
	s_ashr_i32 s8, s2, 5
	v_cndmask_b32_e32 v4, v4, v3, vcc
	v_mul_hi_i32 v3, v0, s78
	v_lshrrev_b32_e32 v6, 31, v3
	v_ashrrev_i32_e32 v3, 5, v3
	v_add_u32_e32 v3, v3, v6
	v_mad_u64_u32 v[6:7], s[4:5], v3, s79, v[0:1]
	s_ashr_i32 s4, s2, 8
	s_ashr_i32 s5, s4, 31
	v_lshl_add_u32 v0, v3, 6, v6
	v_cmp_gt_i32_e32 vcc, 64, v6
	s_lshl_b64 s[20:21], s[4:5], 13
	s_or_b32 s20, s20, s3
	v_cndmask_b32_e32 v0, 0, v0, vcc
	v_cmp_gt_i32_e32 vcc, 13, v189
	s_mul_i32 s4, s21, 0xc00
	s_mul_hi_u32 s5, s20, 0xc00
	v_cndmask_b32_e32 v5, v0, v5, vcc
	v_add_u32_e32 v0, 0xffffcc00, v2
	s_and_b32 s86, s8, 7
	s_add_i32 s5, s5, s4
	s_mul_i32 s4, s20, 0xc00
	v_mul_hi_i32 v2, v0, s78
	s_add_u32 s4, s36, s4
	v_lshrrev_b32_e32 v3, 31, v2
	v_ashrrev_i32_e32 v2, 5, v2
	s_addc_u32 s5, s37, s5
	s_mul_i32 s6, s86, 0x180
	v_add_u32_e32 v6, v2, v3
	s_add_u32 s4, s4, s6
	v_mad_u64_u32 v[2:3], s[6:7], v6, s79, v[0:1]
	v_lshl_add_u32 v0, v6, 6, v2
	v_cmp_gt_i32_e32 vcc, 64, v2
	s_addc_u32 s5, s5, 0
	v_and_b32_e32 v203, 31, v205
	v_cndmask_b32_e32 v0, 0, v0, vcc
	v_cmp_gt_i32_e32 vcc, -3, v189
	v_lshlrev_b32_e32 v186, 5, v189
	v_or_b32_e32 v2, v186, v203
	v_cndmask_b32_e32 v188, v0, v1, vcc
	v_mov_b64_e32 v[0:1], s[4:5]
	s_movk_i32 s4, 0xc00
	v_and_b32_e32 v187, 32, v205
	v_mad_i64_i32 v[0:1], s[4:5], v2, s4, v[0:1]
	v_lshlrev_b32_e32 v184, 1, v187
	v_lshl_or_b32 v207, v4, 16, v5
	v_lshl_add_u64 v[16:17], v[0:1], 0, v[184:185]
	global_load_dwordx4 v[0:3], v[16:17], off
	global_load_dwordx4 v[4:7], v[16:17], off offset:16
	global_load_dwordx4 v[8:11], v[16:17], off offset:32
	global_load_dwordx4 v[12:15], v[16:17], off offset:48
	global_load_dwordx4 v[76:79], v[16:17], off offset:144
	global_load_dwordx4 v[80:83], v[16:17], off offset:128
	global_load_dwordx4 v[92:95], v[16:17], off offset:176
	global_load_dwordx4 v[96:99], v[16:17], off offset:160
	global_load_dwordx4 v[72:75], v[16:17], off offset:272
	global_load_dwordx4 v[100:103], v[16:17], off offset:256
	global_load_dwordx4 v[68:71], v[16:17], off offset:304
	global_load_dwordx4 v[140:143], v[16:17], off offset:288
	v_lshlrev_b32_e32 v245, 2, v187
	global_load_dwordx4 v[112:115], v245, s[18:19] offset:16
	global_load_dwordx4 v[116:119], v245, s[18:19]
	global_load_dwordx4 v[88:91], v245, s[18:19] offset:48
	global_load_dwordx4 v[104:107], v245, s[18:19] offset:32
	global_load_dwordx4 v[64:67], v245, s[18:19] offset:80
	global_load_dwordx4 v[84:87], v245, s[18:19] offset:64
	global_load_dwordx4 v[56:59], v245, s[18:19] offset:112
	global_load_dwordx4 v[60:63], v245, s[18:19] offset:96
	global_load_dwordx4 v[48:51], v245, s[18:19] offset:272
	global_load_dwordx4 v[52:55], v245, s[18:19] offset:256
	global_load_dwordx4 v[40:43], v245, s[18:19] offset:304
	global_load_dwordx4 v[44:47], v245, s[18:19] offset:288
	global_load_dwordx4 v[32:35], v245, s[18:19] offset:336
	global_load_dwordx4 v[36:39], v245, s[18:19] offset:320
	v_lshrrev_b32_e32 v204, 5, v206
	v_lshlrev_b32_e32 v184, 6, v204
	s_mul_i32 s47, s8, 0x18c000
	s_mul_hi_i32 s46, s8, 0x18c000
	s_add_u32 s12, s56, s47
	s_mul_i32 s55, s8, 0x108000
	s_addc_u32 s13, s57, s46
	s_mul_hi_i32 s54, s8, 0x108000
	s_add_u32 s52, s58, s55
	s_addc_u32 s53, s59, s54
	v_readfirstlane_b32 s15, v189
	v_and_b32_e32 v243, 0xffff, v207
	v_lshrrev_b32_e32 v244, 16, v207
	s_lshl_b32 m0, s15, 10
	s_add_u32 s98, s12, 0x0
	s_addc_u32 s99, s13, 0
	s_add_u32 s100, s52, 0x0
	s_addc_u32 s101, s53, 0
	s_add_i32 m0, m0, 0x0
	s_nop 0
	global_load_lds_dwordx4 v243, s[98:99]
	s_lshl_b32 m0, s15, 10
	s_add_i32 m0, m0, 0x2000
	s_cmp_lt_i32 s15, 5
	s_cbranch_scc0 .Latt_pro0_v
	global_load_lds_dwordx4 v244, s[98:99]
	s_branch .Latt_pro0_p2
.Latt_pro0_v:
	global_load_lds_dwordx4 v244, s[100:101]
.Latt_pro0_p2:
	s_cmp_gt_i32 s15, 6
	s_cbranch_scc1 .Latt_pro0_x
	s_lshl_b32 m0, s15, 10
	s_add_i32 m0, m0, 0x4000
	s_nop 0
	global_load_lds_dwordx4 v188, s[100:101]
.Latt_pro0_x:
	s_lshl_b32 m0, s15, 10
	s_add_u32 s98, s12, 0x3000
	s_addc_u32 s99, s13, 0
	s_add_u32 s100, s52, 0x2000
	s_addc_u32 s101, s53, 0
	s_add_i32 m0, m0, 0x5c00
	s_nop 0
	global_load_lds_dwordx4 v243, s[98:99]
	s_lshl_b32 m0, s15, 10
	s_add_i32 m0, m0, 0x7c00
	s_cmp_lt_i32 s15, 5
	s_cbranch_scc0 .Latt_pro1_v
	global_load_lds_dwordx4 v244, s[98:99]
	s_branch .Latt_pro1_p2

.Latt_pro1_p2:
	s_cmp_gt_i32 s15, 6
	s_cbranch_scc1 .Latt_pro1_x
	s_lshl_b32 m0, s15, 10
	s_add_i32 m0, m0, 0x9c00
	s_nop 0
	global_load_lds_dwordx4 v188, s[100:101]
.Latt_pro1_x:
	s_lshl_b32 m0, s15, 10
	s_add_u32 s98, s12, 0x6000
	s_addc_u32 s99, s13, 0
	s_add_u32 s100, s52, 0x4000
	s_addc_u32 s101, s53, 0
	s_add_i32 m0, m0, 0xb800
	s_nop 0
	global_load_lds_dwordx4 v243, s[98:99]
	s_lshl_b32 m0, s15, 10
	s_add_i32 m0, m0, 0xd800
	s_cmp_lt_i32 s15, 5
	s_cbranch_scc0 .Latt_pro2_v
	global_load_lds_dwordx4 v244, s[98:99]
	s_branch .Latt_pro2_p2

.Latt_pro2_p2:
	s_cmp_gt_i32 s15, 6
	s_cbranch_scc1 .Latt_pro2_x
	s_lshl_b32 m0, s15, 10
	s_add_i32 m0, m0, 0xf800
	s_nop 0
	global_load_lds_dwordx4 v188, s[100:101]
.Latt_pro2_x:
	s_cmp_lt_i32 s15, 23
	s_cselect_b64 s[6:7], -1, 0
	s_cmp_gt_i32 s15, 22
	s_waitcnt vmcnt(25)
	v_lshlrev_b32_e32 v215, 16, v0
	v_and_b32_e32 v195, 0xffff0000, v0
	v_or_b32_e32 v0, s3, v203
	v_add_u32_e32 v0, v0, v186
	v_lshlrev_b32_e32 v181, 16, v1
	v_and_b32_e32 v180, 0xffff0000, v1
	v_ashrrev_i32_e32 v1, 31, v0
	v_lshlrev_b64 v[0:1], 8, v[0:1]
	s_waitcnt vmcnt(22)
	v_lshlrev_b32_e32 v214, 16, v12
	v_and_b32_e32 v213, 0xffff0000, v12
	v_lshlrev_b32_e32 v212, 16, v13
	v_and_b32_e32 v211, 0xffff0000, v13
	v_lshlrev_b32_e32 v210, 16, v14
	v_and_b32_e32 v209, 0xffff0000, v14
	v_lshlrev_b32_e32 v208, 16, v15
	v_and_b32_e32 v172, 0xffff0000, v15
	global_load_dwordx4 v[12:15], v245, s[18:19] offset:368
	global_load_dwordx4 v[20:23], v245, s[18:19] offset:352
	v_lshl_add_u64 v[0:1], s[40:41], 0, v[0:1]
	v_lshlrev_b32_e32 v194, 16, v2
	v_and_b32_e32 v193, 0xffff0000, v2
	v_lshlrev_b32_e32 v191, 16, v3
	v_and_b32_e32 v190, 0xffff0000, v3
	v_lshlrev_b32_e32 v192, 16, v4
	v_and_b32_e32 v175, 0xffff0000, v4
	v_lshlrev_b32_e32 v174, 16, v5
	v_and_b32_e32 v173, 0xffff0000, v5
	v_lshlrev_b32_e32 v171, 16, v6
	v_and_b32_e32 v170, 0xffff0000, v6
	v_lshlrev_b32_e32 v169, 16, v7
	v_and_b32_e32 v168, 0xffff0000, v7
	v_lshlrev_b32_e32 v163, 16, v8
	v_and_b32_e32 v162, 0xffff0000, v8
	v_lshlrev_b32_e32 v161, 16, v9
	v_and_b32_e32 v160, 0xffff0000, v9
	v_lshlrev_b32_e32 v167, 16, v10
	v_and_b32_e32 v165, 0xffff0000, v10
	v_lshlrev_b32_e32 v164, 16, v11
	v_and_b32_e32 v166, 0xffff0000, v11
	v_lshl_add_u64 v[108:109], v[0:1], 0, v[184:185]
	global_load_dwordx4 v[120:123], v245, s[18:19] offset:528
	global_load_dwordx4 v[0:3], v245, s[18:19] offset:592
	global_load_dwordx4 v[4:7], v[108:109], off offset:16
	global_load_dwordx4 v[8:11], v[108:109], off offset:144
	global_load_dwordx4 v[150:153], v245, s[18:19] offset:512
	global_load_dwordx4 v[24:27], v245, s[18:19] offset:576
	v_mul_f32_e32 v110, v195, v195
	v_fmac_f32_e32 v110, v215, v215
	v_fmac_f32_e32 v110, v181, v181
	v_fmac_f32_e32 v110, v180, v180
	v_fmac_f32_e32 v110, v194, v194
	v_fmac_f32_e32 v110, v193, v193
	v_fmac_f32_e32 v110, v191, v191
	v_fmac_f32_e32 v110, v190, v190
	v_fmac_f32_e32 v110, v192, v192
	v_fmac_f32_e32 v110, v175, v175
	v_fmac_f32_e32 v110, v174, v174
	v_fmac_f32_e32 v110, v173, v173
	v_fmac_f32_e32 v110, v171, v171
	v_fmac_f32_e32 v110, v170, v170
	v_fmac_f32_e32 v110, v169, v169
	v_fmac_f32_e32 v110, v168, v168
	v_fmac_f32_e32 v110, v163, v163
	v_fmac_f32_e32 v110, v162, v162
	v_fmac_f32_e32 v110, v161, v161
	v_fmac_f32_e32 v110, v160, v160
	v_fmac_f32_e32 v110, v167, v167
	v_fmac_f32_e32 v110, v165, v165
	v_fmac_f32_e32 v110, v164, v164
	v_fmac_f32_e32 v110, v166, v166
	v_fmac_f32_e32 v110, v214, v214
	v_fmac_f32_e32 v110, v213, v213
	v_fmac_f32_e32 v110, v212, v212
	v_fmac_f32_e32 v110, v211, v211
	v_fmac_f32_e32 v110, v210, v210
	v_fmac_f32_e32 v110, v209, v209
	v_fmac_f32_e32 v110, v208, v208
	v_fmac_f32_e32 v110, v172, v172
	s_waitcnt vmcnt(28)
	v_lshlrev_b32_e32 v239, 16, v80
	v_fmac_f32_e32 v110, v239, v239
	v_and_b32_e32 v240, 0xffff0000, v80
	v_fmac_f32_e32 v110, v240, v240
	v_lshlrev_b32_e32 v241, 16, v81
	v_fmac_f32_e32 v110, v241, v241
	v_and_b32_e32 v242, 0xffff0000, v81
	v_fmac_f32_e32 v110, v242, v242
	v_lshlrev_b32_e32 v243, 16, v82
	v_fmac_f32_e32 v110, v243, v243
	v_and_b32_e32 v246, 0xffff0000, v82
	v_fmac_f32_e32 v110, v246, v246
	v_lshlrev_b32_e32 v247, 16, v83
	v_fmac_f32_e32 v110, v247, v247
	v_and_b32_e32 v244, 0xffff0000, v83
	v_fmac_f32_e32 v110, v244, v244
	v_lshlrev_b32_e32 v232, 16, v76
	v_fmac_f32_e32 v110, v232, v232
	v_and_b32_e32 v233, 0xffff0000, v76
	v_fmac_f32_e32 v110, v233, v233
	v_lshlrev_b32_e32 v234, 16, v77
	v_fmac_f32_e32 v110, v234, v234
	v_and_b32_e32 v235, 0xffff0000, v77
	v_fmac_f32_e32 v110, v235, v235
	v_lshlrev_b32_e32 v236, 16, v78
	v_fmac_f32_e32 v110, v236, v236
	v_and_b32_e32 v237, 0xffff0000, v78
	v_fmac_f32_e32 v110, v237, v237
	v_lshlrev_b32_e32 v238, 16, v79
	v_fmac_f32_e32 v110, v238, v238
	v_and_b32_e32 v231, 0xffff0000, v79
	v_fmac_f32_e32 v110, v231, v231
	s_waitcnt vmcnt(26)
	v_lshlrev_b32_e32 v224, 16, v96
	v_fmac_f32_e32 v110, v224, v224
	v_and_b32_e32 v225, 0xffff0000, v96
	v_fmac_f32_e32 v110, v225, v225
	v_lshlrev_b32_e32 v226, 16, v97
	v_fmac_f32_e32 v110, v226, v226
	v_and_b32_e32 v227, 0xffff0000, v97
	v_fmac_f32_e32 v110, v227, v227
	v_lshlrev_b32_e32 v228, 16, v98
	v_fmac_f32_e32 v110, v228, v228
	v_and_b32_e32 v229, 0xffff0000, v98
	v_fmac_f32_e32 v110, v229, v229
	v_lshlrev_b32_e32 v230, 16, v99
	v_fmac_f32_e32 v110, v230, v230
	v_and_b32_e32 v223, 0xffff0000, v99
	v_fmac_f32_e32 v110, v223, v223
	v_lshlrev_b32_e32 v222, 16, v92
	v_and_b32_e32 v221, 0xffff0000, v92
	v_fmac_f32_e32 v110, v222, v222
	v_lshlrev_b32_e32 v220, 16, v93
	v_fmac_f32_e32 v110, v221, v221
	v_and_b32_e32 v219, 0xffff0000, v93
	v_fmac_f32_e32 v110, v220, v220
	v_lshlrev_b32_e32 v218, 16, v94
	v_fmac_f32_e32 v110, v219, v219
	v_and_b32_e32 v217, 0xffff0000, v94
	v_fmac_f32_e32 v110, v218, v218
	v_lshlrev_b32_e32 v216, 16, v95
	v_fmac_f32_e32 v110, v217, v217
	v_and_b32_e32 v184, 0xffff0000, v95
	v_fmac_f32_e32 v110, v216, v216
	s_waitcnt vmcnt(22)
	v_lshlrev_b32_e32 v155, 16, v140
	v_lshlrev_b32_e32 v154, 16, v100
	v_fmac_f32_e32 v110, v184, v184
	v_pk_mul_f32 v[96:97], v[154:155], v[154:155]
	v_and_b32_e32 v157, 0xffff0000, v140
	v_and_b32_e32 v156, 0xffff0000, v100
	s_waitcnt vmcnt(4)
	v_mov_b32_e32 v139, v0
	v_lshlrev_b32_e32 v145, 16, v141
	v_lshlrev_b32_e32 v144, 16, v101
	v_add_f32_e32 v0, v96, v110
	v_pk_mul_f32 v[98:99], v[156:157], v[156:157]
	v_pk_mul_f32 v[92:93], v[144:145], v[144:145]
	v_and_b32_e32 v147, 0xffff0000, v141
	v_and_b32_e32 v146, 0xffff0000, v101
	v_add_f32_e32 v0, v98, v0
	v_lshlrev_b32_e32 v135, 16, v142
	v_lshlrev_b32_e32 v134, 16, v102
	v_pk_mul_f32 v[94:95], v[146:147], v[146:147]
	v_add_f32_e32 v0, v92, v0
	v_pk_mul_f32 v[80:81], v[134:135], v[134:135]
	v_and_b32_e32 v137, 0xffff0000, v142
	v_and_b32_e32 v136, 0xffff0000, v102
	v_add_f32_e32 v0, v94, v0
	v_lshlrev_b32_e32 v125, 16, v143
	v_lshlrev_b32_e32 v124, 16, v103
	v_pk_mul_f32 v[82:83], v[136:137], v[136:137]
	v_add_f32_e32 v0, v80, v0
	v_pk_mul_f32 v[76:77], v[124:125], v[124:125]
	v_and_b32_e32 v127, 0xffff0000, v143
	v_and_b32_e32 v126, 0xffff0000, v103
	v_add_f32_e32 v0, v82, v0
	v_pk_mul_f32 v[78:79], v[126:127], v[126:127]
	v_add_f32_e32 v0, v76, v0
	v_lshlrev_b32_e32 v179, 16, v72
	v_lshlrev_b32_e32 v178, 16, v68
	v_mov_b32_e32 v129, v2
	v_add_f32_e32 v2, v78, v0
	v_and_b32_e32 v183, 0xffff0000, v72
	v_and_b32_e32 v182, 0xffff0000, v68
	v_pk_mul_f32 v[110:111], v[178:179], v[178:179]
	v_pk_mul_f32 v[176:177], v[182:183], v[182:183]
	v_add_f32_e32 v2, v111, v2
	s_waitcnt vmcnt(0)
	v_mov_b32_e32 v149, v26
	v_mov_b32_e32 v26, v153
	v_lshlrev_b32_e32 v153, 16, v73
	v_add_f32_e32 v2, v177, v2
	v_mov_b32_e32 v159, v24
	v_mov_b32_e32 v24, v151
	v_and_b32_e32 v151, 0xffff0000, v73
	v_fmac_f32_e32 v2, v153, v153
	v_lshlrev_b32_e32 v143, 16, v74
	v_fmac_f32_e32 v2, v151, v151
	v_and_b32_e32 v141, 0xffff0000, v74
	v_fmac_f32_e32 v2, v143, v143
	v_lshlrev_b32_e32 v133, 16, v75
	v_fmac_f32_e32 v2, v141, v141
	v_mov_b32_e32 v0, v121
	v_and_b32_e32 v121, 0xffff0000, v75
	v_fmac_f32_e32 v2, v133, v133
	v_fmac_f32_e32 v2, v121, v121
	v_add_f32_e32 v2, v97, v2
	v_add_f32_e32 v2, v99, v2
	global_load_dwordx4 v[16:19], v[108:109], off
	global_load_dwordx4 v[28:31], v[108:109], off offset:128
	v_add_f32_e32 v2, v93, v2
	v_mov_b32_e32 v138, v120
	v_mov_b32_e32 v148, v152
	v_mov_b32_e32 v158, v150
	v_lshlrev_b32_e32 v132, 16, v71
	v_and_b32_e32 v120, 0xffff0000, v71
	v_lshlrev_b32_e32 v142, 16, v70
	v_and_b32_e32 v140, 0xffff0000, v70
	v_lshlrev_b32_e32 v152, 16, v69
	v_and_b32_e32 v150, 0xffff0000, v69
	v_add_f32_e32 v2, v95, v2
	global_load_dwordx4 v[68:71], v[108:109], off offset:176
	global_load_dwordx4 v[72:75], v245, s[18:19] offset:560
	global_load_dwordx4 v[92:95], v245, s[18:19] offset:544
	v_add_f32_e32 v2, v81, v2
	v_add_f32_e32 v2, v83, v2
	v_add_f32_e32 v2, v77, v2
	v_add_f32_e32 v2, v79, v2
	v_add_f32_e32 v2, v110, v2
	v_mov_b32_e32 v110, v150
	v_mov_b32_e32 v111, v152
	v_add_f32_e32 v2, v176, v2
	v_pk_mul_f32 v[110:111], v[110:111], v[110:111]
	s_mov_b32 s3, 0x800000
	v_add_f32_e32 v2, v111, v2
	v_add_f32_e32 v2, v110, v2
	v_mov_b32_e32 v110, v140
	v_mov_b32_e32 v111, v142
	v_pk_mul_f32 v[110:111], v[110:111], v[110:111]
	v_mov_b32_e32 v128, v122
	v_add_f32_e32 v2, v111, v2
	v_add_f32_e32 v2, v110, v2
	v_mov_b32_e32 v110, v120
	v_mov_b32_e32 v111, v132
	v_pk_mul_f32 v[110:111], v[110:111], v[110:111]
	global_load_dwordx4 v[80:83], v245, s[18:19] offset:624
	global_load_dwordx4 v[100:103], v245, s[18:19] offset:608
	v_add_f32_e32 v2, v111, v2
	v_add_f32_e32 v2, v110, v2
	v_mov_b32_e32 v110, v2
	s_nop 1
	v_permlane32_swap_b32_e32 v2, v110
	v_add_f32_e32 v2, v2, v110
	v_fmamk_f32 v2, v2, 0x3baaaaab, v202
	v_mul_f32_e32 v110, 0x4b800000, v2
	v_cmp_gt_f32_e32 vcc, s3, v2
	global_load_dwordx4 v[76:79], v[108:109], off offset:48
	global_load_dwordx4 v[96:99], v[108:109], off offset:32
	v_cndmask_b32_e32 v2, v2, v110, vcc
	v_rsq_f32_e32 v122, v2
	v_mov_b32_e32 v2, v123
	global_load_dwordx4 v[108:111], v[108:109], off offset:160
	v_mov_b32_e32 v176, v4
	v_mul_f32_e32 v123, 0x45800000, v122
	v_cndmask_b32_e32 v122, v122, v123, vcc
	v_mul_f32_e32 v122, 0x3dd53b94, v122
	v_mul_f32_e32 v194, v122, v194
	v_mul_f32_e32 v194, v112, v194
	v_mul_f32_e32 v112, v122, v193
	v_mul_f32_e32 v193, v113, v112
	v_mul_f32_e32 v112, v122, v191
	v_mul_f32_e32 v123, v122, v215
	v_mul_f32_e32 v215, v114, v112
	v_mul_f32_e32 v114, v122, v192
	v_mul_f32_e32 v192, v114, v104
	v_mul_f32_e32 v104, v122, v175
	v_mul_f32_e32 v175, v104, v105
	v_mul_f32_e32 v104, v122, v174
	v_mul_f32_e32 v174, v104, v106
	v_mul_f32_e32 v106, v122, v171
	v_mul_f32_e32 v104, v122, v173
	v_mul_f32_e32 v106, v106, v88
	v_mul_f32_e32 v88, v122, v170
	v_mul_f32_e32 v173, v104, v107
	v_mul_f32_e32 v107, v88, v89
	v_mul_f32_e32 v88, v122, v169
	v_mul_f32_e32 v169, v88, v90
	v_mul_f32_e32 v88, v122, v168
	v_mul_f32_e32 v168, v88, v91
	v_mul_f32_e32 v88, v122, v163
	v_mov_b32_e32 v163, v185
	v_cvt_pk_fp8_f32 v163, v106, v107
	v_mul_f32_e32 v170, v88, v84
	v_mul_f32_e32 v84, v122, v162
	v_mul_f32_e32 v171, v84, v85
	v_cvt_pk_fp8_f32 v163, v169, v168 op_sel:[0,0,1]
	v_mov_b32_e32 v169, v185
	v_mov_b32_e32 v162, v185
	v_cvt_pk_fp8_f32 v162, v192, v175
	v_mov_b32_e32 v175, v185
	v_mul_f32_e32 v123, v116, v123
	v_mul_f32_e32 v116, v122, v195
	v_cvt_pk_fp8_f32 v162, v174, v173 op_sel:[0,0,1]
	v_mov_b32_e32 v173, v185
	s_waitcnt vmcnt(6)
	v_mov_b32_e32 v91, v72
	v_mul_f32_e32 v72, v122, v167
	v_mul_f32_e32 v64, v72, v64
	v_mul_f32_e32 v72, v122, v165
	v_mul_f32_e32 v65, v72, v65
	v_mov_b32_e32 v165, v185
	v_cvt_pk_fp8_f32 v165, v64, v65
	v_mul_f32_e32 v72, v122, v164
	v_mul_f32_e32 v64, v122, v166
	v_mul_f32_e32 v66, v72, v66
	v_mul_f32_e32 v64, v64, v67
	v_cvt_pk_fp8_f32 v165, v66, v64 op_sel:[0,0,1]
	v_mul_f32_e32 v64, v122, v214
	v_mul_f32_e32 v60, v64, v60
	v_mul_f32_e32 v64, v122, v213
	v_mul_f32_e32 v61, v64, v61
	v_mul_f32_e32 v64, v122, v212
	v_mul_f32_e32 v62, v64, v62
	v_mul_f32_e32 v64, v122, v211
	v_mul_f32_e32 v63, v64, v63
	v_mul_f32_e32 v64, v122, v210
	v_mul_f32_e32 v56, v64, v56
	v_mul_f32_e32 v64, v122, v209
	v_mul_f32_e32 v57, v64, v57
	v_mov_b32_e32 v167, v185
	v_cvt_pk_fp8_f32 v167, v56, v57
	v_mul_f32_e32 v64, v122, v208
	v_mul_f32_e32 v56, v122, v172
	v_mul_f32_e32 v58, v64, v58
	v_mul_f32_e32 v56, v56, v59
	v_cvt_pk_fp8_f32 v167, v58, v56 op_sel:[0,0,1]
	v_mul_f32_e32 v56, v122, v239
	v_mul_f32_e32 v52, v56, v52
	v_mul_f32_e32 v56, v122, v240
	v_mul_f32_e32 v53, v56, v53
	v_mul_f32_e32 v56, v122, v241
	v_mul_f32_e32 v54, v56, v54
	v_mul_f32_e32 v56, v122, v242
	v_mul_f32_e32 v55, v56, v55
	v_mul_f32_e32 v56, v122, v243
	v_mul_f32_e32 v48, v56, v48
	v_mul_f32_e32 v56, v122, v246
	v_mul_f32_e32 v49, v56, v49
	v_cvt_pk_fp8_f32 v169, v48, v49
	v_mul_f32_e32 v56, v122, v247
	v_mul_f32_e32 v48, v122, v244
	v_mul_f32_e32 v50, v56, v50
	v_mul_f32_e32 v48, v48, v51
	v_cvt_pk_fp8_f32 v169, v50, v48 op_sel:[0,0,1]
	v_mul_f32_e32 v48, v122, v232
	v_mul_f32_e32 v44, v48, v44
	v_mul_f32_e32 v48, v122, v233
	v_mul_f32_e32 v45, v48, v45
	v_mul_f32_e32 v48, v122, v234
	v_mul_f32_e32 v46, v48, v46
	v_mul_f32_e32 v48, v122, v235
	v_mul_f32_e32 v47, v48, v47
	v_mul_f32_e32 v48, v122, v236
	v_mov_b32_e32 v164, v185
	v_mul_f32_e32 v40, v48, v40
	v_mul_f32_e32 v48, v122, v237
	v_cvt_pk_fp8_f32 v164, v170, v171
	v_mul_f32_e32 v41, v48, v41
	v_mov_b32_e32 v171, v185
	v_cvt_pk_fp8_f32 v171, v40, v41
	v_mul_f32_e32 v48, v122, v238
	v_mul_f32_e32 v40, v122, v231
	v_mul_f32_e32 v42, v48, v42
	v_mul_f32_e32 v40, v40, v43
	v_cvt_pk_fp8_f32 v171, v42, v40 op_sel:[0,0,1]
	v_mul_f32_e32 v40, v122, v224
	v_mul_f32_e32 v36, v40, v36
	v_mul_f32_e32 v40, v122, v225
	v_mul_f32_e32 v37, v40, v37
	v_mul_f32_e32 v40, v122, v226
	v_mul_f32_e32 v38, v40, v38
	v_mul_f32_e32 v40, v122, v227
	v_mul_f32_e32 v39, v40, v39
	v_mul_f32_e32 v40, v122, v228
	v_mul_f32_e32 v32, v40, v32
	v_mul_f32_e32 v40, v122, v229
	v_mul_f32_e32 v33, v40, v33
	v_cvt_pk_fp8_f32 v173, v32, v33
	v_mul_f32_e32 v40, v122, v230
	v_mul_f32_e32 v32, v122, v223
	v_mul_f32_e32 v34, v40, v34
	v_mul_f32_e32 v32, v32, v35
	v_cvt_pk_fp8_f32 v173, v34, v32 op_sel:[0,0,1]
	v_mul_f32_e32 v32, v122, v222
	v_mul_f32_e32 v20, v32, v20
	v_mul_f32_e32 v32, v122, v221
	v_mul_f32_e32 v21, v32, v21
	v_mul_f32_e32 v32, v122, v220
	v_mul_f32_e32 v22, v32, v22
	v_mul_f32_e32 v32, v122, v219
	v_mul_f32_e32 v23, v32, v23
	v_mul_f32_e32 v32, v122, v218
	v_mul_f32_e32 v12, v32, v12
	v_mul_f32_e32 v32, v122, v217
	v_mul_f32_e32 v13, v32, v13
	v_cvt_pk_fp8_f32 v175, v12, v13
	v_mul_f32_e32 v32, v122, v216
	v_mul_f32_e32 v12, v122, v184
	v_mul_f32_e32 v14, v32, v14
	v_mul_f32_e32 v12, v12, v15
	v_mul_f32_e32 v195, v117, v116
	v_mul_f32_e32 v116, v122, v181
	v_cvt_pk_fp8_f32 v175, v14, v12 op_sel:[0,0,1]
	v_pk_mul_f32 v[12:13], v[122:123], v[154:155] op_sel_hi:[0,1]
	v_mul_f32_e32 v118, v118, v116
	v_mul_f32_e32 v116, v122, v180
	v_mov_b32_e32 v180, v16
	v_mov_b32_e32 v181, v28
	v_pk_mul_f32 v[12:13], v[12:13], v[158:159]
	v_mov_b32_e32 v174, v185
	v_pk_mul_f32 v[14:15], v[12:13], v[180:181]
	v_cvt_pk_fp8_f32 v174, v20, v21
	v_sub_f32_e32 v20, v14, v15
	v_mov_b32_e32 v14, v28
	v_mov_b32_e32 v15, v16
	v_pk_mul_f32 v[12:13], v[12:13], v[14:15]
	v_mul_f32_e32 v112, v122, v190
	v_add_f32_e32 v21, v13, v12
	v_pk_mul_f32 v[12:13], v[122:123], v[156:157] op_sel_hi:[0,1]
	v_mov_b32_e32 v190, v17
	v_mov_b32_e32 v191, v29
	v_pk_mul_f32 v[12:13], v[12:13], v[24:25]
	v_mov_b32_e32 v16, v29
	v_pk_mul_f32 v[14:15], v[12:13], v[190:191]
	v_pk_mul_f32 v[12:13], v[12:13], v[16:17]
	v_mul_f32_e32 v119, v119, v116
	v_add_f32_e32 v16, v13, v12
	v_pk_mul_f32 v[12:13], v[122:123], v[144:145] op_sel_hi:[0,1]
	v_mov_b32_e32 v116, v18
	v_mov_b32_e32 v117, v30
	v_pk_mul_f32 v[12:13], v[12:13], v[148:149]
	v_cvt_pk_fp8_f32 v174, v22, v23 op_sel:[0,0,1]
	v_sub_f32_e32 v22, v14, v15
	v_pk_mul_f32 v[14:15], v[12:13], v[116:117]
	v_mul_f32_e32 v245, v115, v112
	v_sub_f32_e32 v17, v14, v15
	v_mov_b32_e32 v14, v30
	v_mov_b32_e32 v15, v18
	v_pk_mul_f32 v[12:13], v[12:13], v[14:15]
	v_mov_b32_e32 v112, v19
	v_add_f32_e32 v23, v13, v12
	v_pk_mul_f32 v[12:13], v[122:123], v[146:147] op_sel_hi:[0,1]
	v_mov_b32_e32 v113, v31
	v_pk_mul_f32 v[12:13], v[12:13], v[26:27]
	v_mov_b32_e32 v18, v31
	v_pk_mul_f32 v[14:15], v[12:13], v[112:113]
	v_pk_mul_f32 v[12:13], v[12:13], v[18:19]
	v_mov_b32_e32 v177, v8
	v_add_f32_e32 v18, v13, v12
	v_pk_mul_f32 v[12:13], v[122:123], v[134:135] op_sel_hi:[0,1]
	v_pk_mul_f32 v[12:13], v[12:13], v[138:139]
	v_sub_f32_e32 v24, v14, v15
	v_pk_mul_f32 v[14:15], v[12:13], v[176:177]
	v_mov_b32_e32 v114, v5
	v_sub_f32_e32 v19, v14, v15
	v_mov_b32_e32 v14, v8
	v_mov_b32_e32 v15, v4
	v_pk_mul_f32 v[12:13], v[12:13], v[14:15]
	v_mov_b32_e32 v115, v9
	v_add_f32_e32 v8, v13, v12
	v_pk_mul_f32 v[12:13], v[122:123], v[136:137] op_sel_hi:[0,1]
	v_pk_mul_f32 v[0:1], v[12:13], v[0:1]
	v_mov_b32_e32 v4, v9
	v_pk_mul_f32 v[12:13], v[0:1], v[114:115]
	v_pk_mul_f32 v[0:1], v[0:1], v[4:5]
	v_mov_b32_e32 v130, v6
	v_add_f32_e32 v9, v1, v0
	v_pk_mul_f32 v[0:1], v[122:123], v[124:125] op_sel_hi:[0,1]
	v_mov_b32_e32 v131, v10
	v_pk_mul_f32 v[0:1], v[0:1], v[128:129]
	v_sub_f32_e32 v12, v12, v13
	v_pk_mul_f32 v[4:5], v[0:1], v[130:131]
	v_mov_b32_e32 v181, v185
	v_sub_f32_e32 v13, v4, v5
	v_mov_b32_e32 v4, v10
	v_mov_b32_e32 v5, v6
	v_pk_mul_f32 v[0:1], v[0:1], v[4:5]
	v_mov_b32_e32 v177, v185
	v_add_f32_e32 v4, v1, v0
	v_pk_mul_f32 v[0:1], v[122:123], v[126:127] op_sel_hi:[0,1]
	v_cvt_pk_fp8_f32 v181, v8, v9
	v_mov_b32_e32 v104, v7
	v_mov_b32_e32 v105, v11
	v_pk_mul_f32 v[0:1], v[0:1], v[2:3]
	v_mov_b32_e32 v6, v11
	v_cvt_pk_fp8_f32 v177, v19, v12
	v_mul_f32_e32 v84, v122, v161
	v_pk_mul_f32 v[2:3], v[0:1], v[104:105]
	v_pk_mul_f32 v[0:1], v[0:1], v[6:7]
	v_mul_f32_e32 v248, v84, v86
	v_mul_f32_e32 v84, v122, v160
	v_mov_b32_e32 v160, v185
	v_mov_b32_e32 v161, v185
	v_add_f32_e32 v0, v1, v0
	v_cvt_pk_fp8_f32 v160, v123, v195
	v_cvt_pk_fp8_f32 v161, v194, v193
	s_waitcnt vmcnt(3)
	v_mov_b32_e32 v194, v100
	v_mov_b32_e32 v195, v92
	v_sub_f32_e32 v2, v2, v3
	v_cvt_pk_fp8_f32 v181, v4, v0 op_sel:[0,0,1]
	v_pk_mul_f32 v[0:1], v[122:123], v[178:179] op_sel_hi:[0,1]
	s_waitcnt vmcnt(1)
	v_mov_b32_e32 v192, v96
	s_waitcnt vmcnt(0)
	v_mov_b32_e32 v193, v108
	v_cvt_pk_fp8_f32 v177, v13, v2 op_sel:[0,0,1]
	v_pk_mul_f32 v[0:1], v[0:1], v[194:195]
	v_mov_b32_e32 v2, v108
	v_mov_b32_e32 v3, v96
	v_pk_mul_f32 v[2:3], v[0:1], v[2:3]
	v_pk_mul_f32 v[0:1], v[0:1], v[192:193]
	v_mov_b32_e32 v92, v101
	v_add_f32_e32 v5, v0, v1
	v_pk_mul_f32 v[0:1], v[122:123], v[182:183] op_sel_hi:[0,1]
	v_pk_mul_f32 v[0:1], v[0:1], v[92:93]
	v_mov_b32_e32 v96, v109
	v_mov_b32_e32 v108, v97
	v_sub_f32_e32 v4, v3, v2
	v_pk_mul_f32 v[2:3], v[0:1], v[96:97]
	v_pk_mul_f32 v[0:1], v[0:1], v[108:109]
	v_cvt_pk_fp8_f32 v160, v118, v119 op_sel:[0,0,1]
	v_mov_b32_e32 v118, v102
	v_mov_b32_e32 v119, v94
	v_add_f32_e32 v7, v0, v1
	v_pk_mul_f32 v[0:1], v[122:123], v[152:153] op_sel_hi:[0,1]
	v_mov_b32_e32 v106, v98
	v_mov_b32_e32 v107, v110
	v_sub_f32_e32 v6, v3, v2
	v_pk_mul_f32 v[0:1], v[0:1], v[118:119]
	v_mov_b32_e32 v2, v110
	v_mov_b32_e32 v3, v98
	v_pk_mul_f32 v[2:3], v[0:1], v[2:3]
	v_pk_mul_f32 v[0:1], v[0:1], v[106:107]
	v_mov_b32_e32 v94, v103
	v_add_f32_e32 v9, v0, v1
	v_pk_mul_f32 v[0:1], v[122:123], v[150:151] op_sel_hi:[0,1]
	v_pk_mul_f32 v[0:1], v[0:1], v[94:95]
	v_mov_b32_e32 v98, v111
	v_mov_b32_e32 v110, v99
	v_sub_f32_e32 v8, v3, v2
	v_pk_mul_f32 v[2:3], v[0:1], v[98:99]
	v_pk_mul_f32 v[0:1], v[0:1], v[110:111]
	v_mov_b32_e32 v90, v80
	v_add_f32_e32 v11, v0, v1
	v_pk_mul_f32 v[0:1], v[122:123], v[142:143] op_sel_hi:[0,1]
	v_mov_b32_e32 v88, v76
	v_mov_b32_e32 v89, v68
	v_sub_f32_e32 v10, v3, v2
	v_pk_mul_f32 v[0:1], v[0:1], v[90:91]
	v_mov_b32_e32 v2, v68
	v_mov_b32_e32 v3, v76
	v_pk_mul_f32 v[2:3], v[0:1], v[2:3]
	v_pk_mul_f32 v[0:1], v[0:1], v[88:89]
	v_mov_b32_e32 v72, v81
	v_add_f32_e32 v13, v0, v1
	v_pk_mul_f32 v[0:1], v[122:123], v[140:141] op_sel_hi:[0,1]
	v_mov_b32_e32 v176, v185
	v_pk_mul_f32 v[0:1], v[0:1], v[72:73]
	v_mov_b32_e32 v76, v69
	v_mov_b32_e32 v68, v77
	v_cvt_pk_fp8_f32 v176, v20, v22
	v_sub_f32_e32 v12, v3, v2
	v_pk_mul_f32 v[2:3], v[0:1], v[76:77]
	v_pk_mul_f32 v[0:1], v[0:1], v[68:69]
	v_mul_f32_e32 v249, v84, v87
	v_mov_b32_e32 v86, v82
	v_mov_b32_e32 v87, v74
	v_add_f32_e32 v15, v0, v1
	v_pk_mul_f32 v[0:1], v[122:123], v[132:133] op_sel_hi:[0,1]
	v_mov_b32_e32 v84, v78
	v_mov_b32_e32 v85, v70
	v_sub_f32_e32 v14, v3, v2
	v_pk_mul_f32 v[0:1], v[0:1], v[86:87]
	v_mov_b32_e32 v2, v70
	v_mov_b32_e32 v3, v78
	v_mov_b32_e32 v166, v185
	v_mov_b32_e32 v168, v185
	v_mov_b32_e32 v170, v185
	v_mov_b32_e32 v172, v185
	v_mov_b32_e32 v180, v185
	v_pk_mul_f32 v[2:3], v[0:1], v[2:3]
	v_pk_mul_f32 v[0:1], v[0:1], v[84:85]
	v_mov_b32_e32 v178, v185
	v_mov_b32_e32 v179, v185
	v_mov_b32_e32 v182, v185
	v_mov_b32_e32 v183, v185
	v_cvt_pk_fp8_f32 v166, v60, v61
	v_cvt_pk_fp8_f32 v168, v52, v53
	v_cvt_pk_fp8_f32 v170, v44, v45
	v_cvt_pk_fp8_f32 v172, v36, v37
	v_cvt_pk_fp8_f32 v180, v21, v16
	v_cvt_pk_fp8_f32 v176, v17, v24 op_sel:[0,0,1]
	v_add_f32_e32 v17, v0, v1
	v_pk_mul_f32 v[0:1], v[122:123], v[120:121] op_sel_hi:[0,1]
	v_mov_b32_e32 v74, v83
	v_cvt_pk_fp8_f32 v178, v4, v6
	v_cvt_pk_fp8_f32 v179, v12, v14
	v_cvt_pk_fp8_f32 v182, v5, v7
	v_cvt_pk_fp8_f32 v183, v13, v15
	v_pk_mul_f32 v[0:1], v[0:1], v[74:75]
	v_mov_b32_e32 v78, v71
	v_mov_b32_e32 v70, v79
	v_sub_f32_e32 v16, v3, v2
	v_pk_mul_f32 v[2:3], v[0:1], v[78:79]
	v_pk_mul_f32 v[0:1], v[0:1], v[70:71]
	v_sub_f32_e32 v2, v3, v2
	v_add_f32_e32 v0, v0, v1
	v_cvt_pk_fp8_f32 v161, v215, v245 op_sel:[0,0,1]
	v_cvt_pk_fp8_f32 v164, v248, v249 op_sel:[0,0,1]
	v_cvt_pk_fp8_f32 v166, v62, v63 op_sel:[0,0,1]
	v_cvt_pk_fp8_f32 v168, v54, v55 op_sel:[0,0,1]
	v_cvt_pk_fp8_f32 v170, v46, v47 op_sel:[0,0,1]
	v_cvt_pk_fp8_f32 v172, v38, v39 op_sel:[0,0,1]
	v_cvt_pk_fp8_f32 v180, v23, v18 op_sel:[0,0,1]
	v_cvt_pk_fp8_f32 v178, v8, v10 op_sel:[0,0,1]
	v_cvt_pk_fp8_f32 v179, v16, v2 op_sel:[0,0,1]
	v_cvt_pk_fp8_f32 v182, v9, v11 op_sel:[0,0,1]
	v_cvt_pk_fp8_f32 v183, v17, v0 op_sel:[0,0,1]
	v_and_b32_e32 v184, 0xffff, v207
	s_cbranch_scc1 .LBB0_808
	s_lshl_b32 s3, s15, 10
	s_add_i32 m0, s3, 0
	s_cmp_lt_i32 s15, 13
	s_cselect_b32 s5, s13, s53
	s_cselect_b32 s4, s12, s52
	s_nop 0
.LBB0_808:
	s_add_i32 s14, s15, 8
	s_cmp_lt_i32 s15, 15
	s_cselect_b64 s[8:9], -1, 0
	s_cmp_gt_i32 s15, 14
	v_lshrrev_b32_e32 v190, 16, v207
	s_cbranch_scc1 .LBB0_810
	s_lshl_b32 s3, s14, 10
	s_add_i32 m0, s3, 0
	s_cmp_lt_i32 s15, 5
	s_cselect_b32 s5, s13, s53
	s_cselect_b32 s4, s12, s52
	s_nop 0
.LBB0_810:
	s_add_i32 s70, s15, 16
	s_cmp_lt_i32 s15, 7
	s_cselect_b64 s[10:11], -1, 0
	s_cmp_gt_i32 s15, 6
	s_cbranch_scc1 .LBB0_812
	s_lshl_b32 s3, s70, 10
	s_add_i32 m0, s3, 0
	s_cmp_lt_i32 s15, -3
	s_cselect_b32 s5, s13, s53
	s_cselect_b32 s4, s12, s52
	s_nop 0
.LBB0_812:
	s_add_u32 s3, s12, 0x3000
	s_addc_u32 s62, s13, 0
	s_add_u32 s63, s52, 0x2000
	v_cndmask_b32_e64 v0, 0, 1, s[6:7]
	s_addc_u32 s66, s53, 0
	v_cmp_ne_u32_e64 s[4:5], 1, v0
	s_andn2_b64 vcc, exec, s[6:7]
	s_cbranch_vccnz .LBB0_836
	s_lshl_b32 s6, s15, 10
	s_add_i32 s6, s6, 0
	s_add_i32 m0, s6, 0x5c00
	s_cmp_lt_i32 s15, 13
	s_cselect_b32 s7, s62, s66
	s_cselect_b32 s6, s3, s63
	s_nop 0
	v_cndmask_b32_e64 v0, 0, 1, s[8:9]
	v_cmp_ne_u32_e64 s[6:7], 1, v0
	s_andn2_b64 vcc, exec, s[8:9]
	s_cbranch_vccz .LBB0_837

.LBB0_815:
	s_lshl_b32 s10, s70, 10
	s_add_i32 s10, s10, 0
	s_add_i32 m0, s10, 0x5c00
	s_cmp_lt_i32 s15, -3
	s_cselect_b32 s11, s62, s66
	s_cselect_b32 s10, s3, s63
	s_nop 0
.LBB0_816:
	s_add_u32 s3, s12, 0x6000
	s_addc_u32 s10, s13, 0
	s_add_u32 s11, s52, 0x4000
	s_addc_u32 s62, s53, 0
	s_and_b64 vcc, exec, s[4:5]
	s_cbranch_vccnz .LBB0_838
	s_lshl_b32 s48, s15, 10
	s_add_i32 s48, s48, 0
	s_add_i32 m0, s48, 0xb800
	s_cmp_lt_i32 s15, 13
	s_cselect_b32 s49, s10, s62
	s_cselect_b32 s48, s3, s11
	s_nop 0
	s_and_b64 vcc, exec, s[6:7]
	s_cbranch_vccz .LBB0_839

.LBB0_819:
	s_lshl_b32 s48, s70, 10
	s_add_i32 s48, s48, 0
	s_add_i32 m0, s48, 0xb800
	s_cmp_lt_i32 s15, -3
	s_cselect_b32 s49, s10, s62
	s_cselect_b32 s48, s3, s11
	s_nop 0

.LBB0_837:
	s_lshl_b32 s8, s14, 10
	s_add_i32 s8, s8, 0
	s_add_i32 m0, s8, 0x5c00
	s_cmp_lt_i32 s15, 5
	s_cselect_b32 s9, s62, s66
	s_cselect_b32 s8, s3, s63
	s_nop 0
	v_cndmask_b32_e64 v0, 0, 1, s[10:11]
	v_cmp_ne_u32_e64 s[8:9], 1, v0
	s_andn2_b64 vcc, exec, s[10:11]
	s_cbranch_vccz .LBB0_815
	s_branch .LBB0_816

.LBB0_839:
	s_lshl_b32 s48, s14, 10
	s_add_i32 s48, s48, 0
	s_add_i32 m0, s48, 0xb800
	s_cmp_lt_i32 s15, 5
	s_cselect_b32 s49, s10, s62
	s_cselect_b32 s48, s3, s11
	s_nop 0
	s_and_b64 vcc, exec, s[8:9]
	s_cbranch_vccz .LBB0_819
	s_branch .LBB0_820
